# v34 + in-proj SW mainloop: LDS-DMA issue (M0 add, address add, load) interleaved one per MFMA instead of a separate issue block at the loop head
# baseline (speedup 1.0000x reference)
; __device__ __forceinline__ f32x16 mfma32(bf16x8 a, bf16x8 b, f32x16 c) { return __builtin_amdgcn_mfma_f32_32x32x16_bf16(a, b, c, 0, 0, 0); }
; template <bool SW>
; __device__ __forceinline__ void gemm_mainloop(const bf16_t* __restrict__ A, int lda, const bf16_t* __restrict__ Bt, int ldb, int K,
;                                               f32x16 (&acc)[2][2], char* lds, int kstart) {
;     ...
;   for (int kt = 0; kt < nk; ++kt) {
;     const bool more = (kt + 1 < nk);
;     if (more) {
;       char* d = ldst + ((kt + 1) & 1) * GEMM_BUF;
;       const int ko = ((kt + 1 + kstart) & (nk - 1)) * 64;
; #pragma unroll
;       for (int i = 0; i < 4; ++i) { glds16(ap[i] + ko, d + i * 1024); glds16(bp[i] + ko, d + 16384 + i * 1024); }
;     }
;     const char* base = lds + (kt & 1) * GEMM_BUF;
; #pragma unroll
;     for (int ks = 0; ks < 4; ++ks) {
;       const int co = ((2 * ks + hh) ^ swz) * 16;
;       bf16x8 a0 = *(const bf16x8*)(base + roffA + co), a1 = *(const bf16x8*)(base + roffA + 32 * 128 + co);
;       bf16x8 b0 = *(const bf16x8*)(base + roffB + co), b1 = *(const bf16x8*)(base + roffB + 32 * 128 + co);
;       if (SW) {
;         acc[0][0] = mfma32(b0, a0, acc[0][0]); acc[0][1] = mfma32(b1, a0, acc[0][1]);
;         acc[1][0] = mfma32(b0, a1, acc[1][0]); acc[1][1] = mfma32(b1, a1, acc[1][1]);
;       } else {
;         acc[0][0] = mfma32(a0, b0, acc[0][0]); acc[0][1] = mfma32(a0, b1, acc[0][1]);
;         acc[1][0] = mfma32(a1, b0, acc[1][0]); acc[1][1] = mfma32(a1, b1, acc[1][1]);
;       }
;     }
;     asm volatile("s_waitcnt vmcnt(0)" ::: "memory");
;     __syncthreads();
;   }
.LBB0_176:
	s_add_i32 s35, s34, 0x8000
	s_cmp_lt_u32 s3, 15
	s_cbranch_scc0 .LBB0_175
	s_and_b32 s0, s34, 0x8000
	v_or_b32_e32 v109, s0, v150
	v_add_u32_e32 v111, v109, v151
	ds_read_b128 v[138:141], v111 offset:16384
	ds_read_b128 v[168:171], v111 offset:20480
	v_add_u32_e32 v113, s0, v149
	s_and_b32 s0, s35, 0x8000
	v_readfirstlane_b32 s1, v147
	s_and_b32 s76, s2, 0x3c0
	s_lshl_b32 s76, s76, 1
	s_add_i32 s0, s0, s1
	v_add_u32_e32 v115, v113, v151
	ds_read_b128 v[164:167], v115
	v_add_u32_e32 v111, v109, v152
	s_add_i32 s3, s3, 1
	s_add_i32 s2, s2, 64
	s_waitcnt lgkmcnt(0)
	v_mfma_f32_32x32x16_bf16 v[48:63], v[138:141], v[164:167], v[48:63]
	s_mov_b32 m0, s0
	v_lshl_add_u64 v[210:211], v[116:117], 0, s[76:77]
	global_load_lds_dwordx4 v[210:211], off
	s_mov_b32 s34, s35
	v_mfma_f32_32x32x16_bf16 v[32:47], v[168:171], v[164:167], v[32:47]
	s_add_i32 m0, s0, 0x4000
	v_lshl_add_u64 v[210:211], v[130:131], 0, s[76:77]
	global_load_lds_dwordx4 v[210:211], off
	ds_read_b128 v[164:167], v115 offset:4096
	v_add_u32_e32 v115, v113, v152
	s_waitcnt lgkmcnt(0)
	v_mfma_f32_32x32x16_bf16 v[16:31], v[138:141], v[164:167], v[16:31]
	s_add_i32 m0, s0, 0x400
	v_lshl_add_u64 v[210:211], v[118:119], 0, s[76:77]
	global_load_lds_dwordx4 v[210:211], off
	ds_read_b128 v[138:141], v111 offset:16384
	v_mfma_f32_32x32x16_bf16 v[0:15], v[168:171], v[164:167], v[0:15]
	s_add_i32 m0, s0, 0x4400
	v_lshl_add_u64 v[210:211], v[132:133], 0, s[76:77]
	global_load_lds_dwordx4 v[210:211], off
	ds_read_b128 v[168:171], v111 offset:20480
	ds_read_b128 v[164:167], v115
	v_add_u32_e32 v111, v109, v153
	v_add_u32_e32 v109, v109, v154
	s_waitcnt lgkmcnt(0)
	v_mfma_f32_32x32x16_bf16 v[48:63], v[138:141], v[164:167], v[48:63]
	s_add_i32 m0, s0, 0x800
	v_lshl_add_u64 v[210:211], v[120:121], 0, s[76:77]
	global_load_lds_dwordx4 v[210:211], off
	v_mfma_f32_32x32x16_bf16 v[32:47], v[168:171], v[164:167], v[32:47]
	s_add_i32 m0, s0, 0x4800
	v_lshl_add_u64 v[210:211], v[134:135], 0, s[76:77]
	global_load_lds_dwordx4 v[210:211], off
	ds_read_b128 v[164:167], v115 offset:4096
	v_add_u32_e32 v115, v113, v153
	s_waitcnt lgkmcnt(0)
	v_mfma_f32_32x32x16_bf16 v[16:31], v[138:141], v[164:167], v[16:31]
	s_add_i32 m0, s0, 0xc00
	v_lshl_add_u64 v[210:211], v[122:123], 0, s[76:77]
	global_load_lds_dwordx4 v[210:211], off
	ds_read_b128 v[138:141], v111 offset:16384
	v_mfma_f32_32x32x16_bf16 v[0:15], v[168:171], v[164:167], v[0:15]
	s_add_i32 m0, s0, 0x4c00
	v_lshl_add_u64 v[210:211], v[136:137], 0, s[76:77]
	global_load_lds_dwordx4 v[210:211], off
	ds_read_b128 v[168:171], v111 offset:20480
	ds_read_b128 v[164:167], v115
	v_add_u32_e32 v111, v113, v154
	s_waitcnt lgkmcnt(0)
	v_mfma_f32_32x32x16_bf16 v[48:63], v[138:141], v[164:167], v[48:63]
	v_mfma_f32_32x32x16_bf16 v[32:47], v[168:171], v[164:167], v[32:47]
	ds_read_b128 v[164:167], v115 offset:4096
	s_waitcnt lgkmcnt(0)
	v_mfma_f32_32x32x16_bf16 v[16:31], v[138:141], v[164:167], v[16:31]
	ds_read_b128 v[138:141], v109 offset:16384
	v_mfma_f32_32x32x16_bf16 v[0:15], v[168:171], v[164:167], v[0:15]
	ds_read_b128 v[168:171], v109 offset:20480
	ds_read_b128 v[164:167], v111
	s_waitcnt lgkmcnt(0)
	v_mfma_f32_32x32x16_bf16 v[48:63], v[138:141], v[164:167], v[48:63]
	v_mfma_f32_32x32x16_bf16 v[32:47], v[168:171], v[164:167], v[32:47]
	ds_read_b128 v[164:167], v111 offset:4096
	s_waitcnt vmcnt(0)
	s_waitcnt lgkmcnt(0)
	s_barrier
	v_mfma_f32_32x32x16_bf16 v[16:31], v[138:141], v[164:167], v[16:31]
	v_mfma_f32_32x32x16_bf16 v[0:15], v[168:171], v[164:167], v[0:15]
	s_cmp_lg_u32 s3, 16
	s_cbranch_scc0 .LBB0_180
	s_branch .LBB0_176
